# inproj tile map: column position inside a 4-wide column group rotates with the round index (on top of v27)
# baseline (speedup 1.0000x reference)
; DI int tidx() { int t = threadIdx.x; asm volatile("" : "+v"(t)); return t; }
; #define TASK_LOOP(t, nt, base) for (int t = (int)((blockIdx.x + gridDim.x - ((unsigned)(base) % gridDim.x)) % gridDim.x); t < (nt); t += gridDim.x)
; #define STAGEA(P, br, kt) STAGE_(P, A, br, kt, so0, so1)
; #define STAGEB(P, br, kt) STAGE_(P, Bt, br, kt, sb0, sb1)
; template <bool PERM, class EPI>
; DI void gemm256(LAS u16* shm, const u16* __restrict__ A, const u16* __restrict__ Bt, int K, int brow, int bcol, bool pre, bool has_next, int nbrow, int nbcol, EPI epi) {
;     ...
;   const int tid = tidx();
;   const int wid = __builtin_amdgcn_readfirstlane(tid >> 6), lane = tid & 63, wr = wid >> 2, wc = wid & 3, fr = lane & 15, fq = lane >> 4;
;   int r0, c0, r1, c1;
;   stage_rc(tid * 16, r0, c0);
;   stage_rc(tid * 16 + 8192, r1, c1);
;   const int ra0 = PERM ? ((r0 & ~31) + perm32(r0 & 31)) : r0, ra1 = PERM ? ((r1 & ~31) + perm32(r1 & 31)) : r1;
;   const unsigned so0 = (unsigned)(ra0 * K + c0) * 2u, so1 = (unsigned)(ra1 * K + c1) * 2u;
;   const unsigned sb0 = (unsigned)(r0 * K + c0) * 2u, sb1 = (unsigned)(r1 * K + c1) * 2u;
;   const unsigned ldsw = (unsigned)wid * 1024u;
;   const int lb = ((fr * 64 + fq * 16) ^ ((fr >> 3) << 5));
;     ...
;   f32x4 acc[2][2][4][2];
; #pragma unroll
;   for (int a = 0; a < 2; ++a)
; #pragma unroll
;     for (int b = 0; b < 2; ++b)
; #pragma unroll
;       for (int m = 0; m < 4; ++m)
; #pragma unroll
;         for (int n = 0; n < 2; ++n) { acc[a][b][m][n][0] = 0.f; acc[a][b][m][n][1] = 0.f; acc[a][b][m][n][2] = 0.f; acc[a][b][m][n][3] = 0.f; }
;   bf16x8 At[4][2], B0[2][2], B1[2][2];
;   const int nt = K / 64;
;   if (!pre) {
;     STAGEB(SB(0, 0), bcol, 0); STAGEA(SA(0, 0), brow, 0);
;     STAGEB(SB(0, 1), bcol + 128, 0); STAGEA(SA(0, 1), brow + 128, 0);
;   }
; DI void phase_inproj(const Prm& p, unsigned char* smem_raw, int l, int S, int& base) {
;     ...
;   TASK_LOOP(t, 32 * 64, base) {
;     int tn, tm;
;     map256(t, 32, tn, tm);
;     const int brow = tn * 256, bcol = tm * 256;
;     const int tnx = t + (int)gridDim.x;
;     const bool has_next = tnx < (32 * 64);
;     int tn2 = 0, tm2 = 0;
;     if (has_next) map256(tnx, 32, tn2, tm2);
;     const int nbrow = tn2 * 256, nbcol = tm2 * 256;
;     const bool hn = has_next && ((tn2 != 16) == (tn != 16));
.LBB0_426:
	s_add_i32 s31, s7, s30
	s_cmpk_lt_i32 s31, 0x800
	s_cselect_b64 s[0:1], -1, 0
	s_cmpk_gt_i32 s31, 0x7ff
	s_cselect_b64 s[2:3], -1, 0
	v_writelane_b32 v255, s2, 30
	s_mov_b32 s58, 0
	s_and_b64 vcc, exec, s[2:3]
	v_writelane_b32 v255, s3, 31
	s_mov_b32 s2, 0
	s_cbranch_vccnz .LBB0_428
	s_ashr_i32 s2, s31, 5
	s_and_b32 s2, s2, -8
	s_and_b32 s3, s31, 7
	s_or_b32 s2, s2, s3
	s_ashr_i32 s3, s31, 31
	s_lshr_b32 s3, s3, 29
	s_add_i32 s3, s2, s3
	s_ashr_i32 s3, s3, 3
	s_add_i32 s2, s3, s2
	s_lshr_b32 s4, s2, 29
	s_add_i32 s4, s2, s4
	s_and_b32 s4, s4, 0x3ffffff8
	s_sub_i32 s2, s2, s4
	s_lshl_b32 s2, s2, 2
	s_lshr_b32 s4, s31, 3
	s_lshr_b32 s98, s31, 8
	s_add_i32 s4, s4, s98
	s_and_b32 s4, s4, 3
	s_or_b32 s2, s2, s4
	s_lshl_b32 s4, s31, 3
	s_lshl_b32 s3, s3, 11
	s_and_b32 s4, s4, 0x700
	s_or_b32 s58, s3, s4
.LBB0_428:
	s_ashr_i32 s3, s7, 5
	s_and_b32 s3, s3, -8
	s_and_b32 s6, s7, 7
	s_or_b32 s3, s3, s6
	s_ashr_i32 s6, s7, 31
	s_lshr_b32 s6, s6, 29
	s_add_i32 s6, s3, s6
	s_ashr_i32 s6, s6, 3
	s_add_i32 s3, s6, s3
	s_lshr_b32 s52, s3, 29
	s_add_i32 s52, s3, s52
	s_and_b32 s52, s52, -8
	s_sub_i32 s61, s3, s52
	s_lshl_b32 s3, s61, 2
	s_lshr_b32 s52, s7, 3
	s_lshr_b32 s98, s7, 8
	s_add_i32 s52, s52, s98
	s_and_b32 s52, s52, 3
	s_or_b32 s53, s3, s52
	s_lshl_b32 s3, s7, 3
	s_lshl_b32 s70, s6, 11
	s_and_b32 s3, s3, 0x700
	s_xor_b64 s[4:5], s[20:21], -1
	s_and_b32 s63, s66, 0x700
	s_lshl_b32 s64, s53, 8
	s_or_b32 s52, s70, s3
	s_lshl_b32 s6, s2, 8
	s_cmp_lg_u32 s2, 16
	s_cselect_b64 s[2:3], -1, 0
	s_cmp_eq_u32 s53, 16
	s_cselect_b64 s[54:55], -1, 0
	s_xor_b64 s[20:21], s[54:55], s[2:3]
	s_and_b64 s[0:1], s[0:1], s[20:21]
	v_writelane_b32 v255, s0, 32
	v_cndmask_b32_e64 v0, 0, 1, s[4:5]
	s_mov_b64 s[2:3], -1
	v_writelane_b32 v255, s1, 33
	s_and_b64 vcc, exec, s[54:55]
	v_cmp_ne_u32_e64 s[0:1], 1, v0
	s_cbranch_vccnz .LBB0_586
	v_mov_b32_e32 v16, v224
	s_mov_b64 s[88:89], s[20:21]
	v_bfe_i32 v3, v16, 27, 1
	v_lshlrev_b32_e32 v0, 4, v16
	v_lshrrev_b32_e32 v3, 22, v3
	v_add_u32_e32 v3, v0, v3
	v_and_b32_e32 v3, 0xfffffc00, v3
	v_sub_u32_e32 v3, v0, v3
	v_ashrrev_i32_e32 v2, 31, v16
	v_lshrrev_b32_e32 v4, 4, v3
	v_lshrrev_b32_e32 v2, 26, v2
	v_bitop3_b32 v4, v4, v3, 32 bitop3:0x6c
	v_ashrrev_i32_e32 v3, 31, v3
	v_add_u32_e32 v2, v16, v2
	v_lshrrev_b32_e32 v3, 26, v3
	v_ashrrev_i32_e32 v2, 6, v2
	v_add_u32_e32 v3, v4, v3
	v_ashrrev_i32_e32 v8, 6, v3
	v_lshlrev_b32_e32 v3, 5, v2
	v_and_b32_e32 v13, 32, v3
	v_mul_i32_i24_e32 v3, 64, v8
	v_sub_u32_e32 v3, v4, v3
	v_ashrrev_i16_sdwa v3, v230, sext(v3) dst_sel:DWORD dst_unused:UNUSED_PAD src0_sel:DWORD src1_sel:BYTE_0
	v_add_u32_e32 v0, 0x2000, v0
	v_bfe_i32 v11, v3, 0, 16
	v_ashrrev_i32_e32 v3, 31, v0
	v_lshrrev_b32_e32 v3, 22, v3
	v_add_u32_e32 v3, v0, v3
	v_ashrrev_i32_e32 v4, 10, v3
	v_mul_i32_i24_e32 v3, 0x400, v4
	v_sub_u32_e32 v0, v0, v3
	v_lshlrev_b32_e32 v5, 3, v2
	v_lshrrev_b32_e32 v3, 4, v0
	v_and_b32_e32 v5, -16, v5
	v_bitop3_b32 v0, v3, v0, 32 bitop3:0x6c
	v_add_u32_e32 v17, v8, v5
	v_ashrrev_i32_e32 v5, 31, v0
	v_lshrrev_b32_e32 v5, 26, v5
	v_lshlrev_b32_e32 v3, 3, v4
	v_add_u32_e32 v5, v0, v5
	v_and_b32_e32 v3, -16, v3
	v_ashrrev_i32_e32 v14, 6, v5
	v_add_u32_e32 v18, v14, v3
	v_lshlrev_b32_e32 v3, 5, v4
	v_and_b32_e32 v19, 32, v3
	v_and_b32_e32 v3, 0xc0, v5
	v_sub_u32_e32 v0, v0, v3
	v_ashrrev_i16_sdwa v0, v230, sext(v0) dst_sel:DWORD dst_unused:UNUSED_PAD src0_sel:DWORD src1_sel:BYTE_0
	v_bfe_i32 v15, v0, 0, 16
	v_lshlrev_b32_e32 v0, 1, v17
	v_and_b32_e32 v7, 0x1fffe0, v17
	v_and_b32_e32 v9, 24, v0
	v_lshrrev_b32_e32 v0, 2, v17
	v_and_b32_e32 v12, 3, v8
	v_and_b32_e32 v10, 4, v0
	v_or_b32_e32 v0, v7, v12
	v_and_b32_e32 v3, 0x1fffe0, v18
	v_lshlrev_b32_e32 v20, 1, v18
	v_lshrrev_b32_e32 v5, 2, v18
	v_and_b32_e32 v6, 3, v14
	v_readfirstlane_b32 s4, v16
	v_or3_b32 v0, v0, v10, v9
	v_and_b32_e32 v5, 4, v5
	v_or_b32_e32 v21, v3, v6
	v_add_lshl_u32 v22, v13, v11, 1
	v_and_b32_e32 v13, 24, v20
	s_ashr_i32 s2, s4, 6
	s_waitcnt vmcnt(10)
	v_lshl_add_u32 v130, v0, 11, v22
	v_add_lshl_u32 v19, v19, v15, 1
	v_or3_b32 v0, v21, v5, v13
	s_lshl_b32 s5, s2, 10
	v_lshl_add_u32 v132, v0, 11, v19
	v_lshl_add_u32 v0, v17, 11, v22
	s_and_b64 vcc, exec, s[0:1]
	s_waitcnt vmcnt(9)
	v_lshl_add_u32 v134, v18, 11, v19
	s_cbranch_vccnz .LBB0_431
	v_readlane_b32 s36, v253, 8
	s_ashr_i32 s53, s52, 31
	v_readlane_b32 s48, v253, 20
	v_readlane_b32 s49, v253, 21
	s_lshl_b64 s[54:55], s[52:53], 11
	v_readlane_b32 s50, v253, 22
	v_readlane_b32 s51, v253, 23
	s_mov_b64 s[20:21], s[48:49]
	s_add_u32 s54, s20, s54
	s_addc_u32 s55, s21, s55
	s_add_i32 m0, s5, 0x10000
	s_ashr_i32 s65, s64, 31
	global_load_lds_dwordx4 v0, s[54:55]
	s_add_i32 m0, s5, 0x12000
	v_readlane_b32 s8, v255, 19
	global_load_lds_dwordx4 v134, s[54:55]
	s_lshl_b64 s[54:55], s[64:65], 11
	v_readlane_b32 s9, v255, 20
	s_add_u32 s54, s8, s54
	s_addc_u32 s55, s9, s55
	s_mov_b32 m0, s5
	v_readlane_b32 s37, v253, 9
	global_load_lds_dwordx4 v130, s[54:55]
	s_add_i32 m0, s5, 0x2000
	v_readlane_b32 s38, v253, 10
	global_load_lds_dwordx4 v132, s[54:55]
	s_or_b32 s54, s52, 0x80
	s_ashr_i32 s55, s54, 31
	s_lshl_b64 s[54:55], s[54:55], 11
	s_add_u32 s54, s20, s54
	s_addc_u32 s55, s21, s55
	s_add_i32 m0, s5, 0x14000
	v_readlane_b32 s39, v253, 11
	global_load_lds_dwordx4 v0, s[54:55]
	s_add_i32 m0, s5, 0x16000
	v_readlane_b32 s40, v253, 12
	global_load_lds_dwordx4 v134, s[54:55]
	s_or_b32 s54, s64, 0x80
	s_ashr_i32 s55, s54, 31
	s_lshl_b64 s[54:55], s[54:55], 11
	s_add_u32 s54, s8, s54
	s_addc_u32 s55, s9, s55
	s_add_i32 m0, s5, 0x4000
	v_readlane_b32 s41, v253, 13
	global_load_lds_dwordx4 v130, s[54:55]
	s_add_i32 m0, s5, 0x6000
	v_readlane_b32 s42, v253, 14
	global_load_lds_dwordx4 v132, s[54:55]
	v_readlane_b32 s43, v253, 15
	v_readlane_b32 s44, v253, 16
	v_readlane_b32 s45, v253, 17
	v_readlane_b32 s46, v253, 18
	v_readlane_b32 s47, v253, 19
	s_mov_b64 s[22:23], s[50:51]

; #define STAGEA(P, br, kt) STAGE_(P, A, br, kt, so0, so1)
; #define STAGEB(P, br, kt) STAGE_(P, Bt, br, kt, sb0, sb1)
; #define WAIT_V(n) asm volatile("s_waitcnt vmcnt(" #n ")" ::: "memory")
; #define BAR __builtin_amdgcn_s_barrier()
; template <bool PERM, class EPI>
; DI void gemm256(LAS u16* shm, const u16* __restrict__ A, const u16* __restrict__ Bt, int K, int brow, int bcol, bool pre, bool has_next, int nbrow, int nbcol, EPI epi) {
;     ...
;   if (wr == 1) BAR;
;   WAIT_V(4); BAR;
;   STAGEB(SB(1, 0), bcol, 1); STAGEA(SA(1, 0), brow, 1); STAGEB(SB(1, 1), bcol + 128, 1);
.LBB0_433:
	s_lshr_b32 s3, s7, 3
	s_lshr_b32 s98, s7, 8
	s_add_i32 s3, s3, s98
	v_readlane_b32 s36, v253, 8
	s_and_b32 s55, s2, 3
	s_and_b32 s2, s3, 3
	s_ashr_i32 s53, s52, 31
	v_readlane_b32 s48, v253, 20
	v_readlane_b32 s49, v253, 21
	s_lshl_b32 s62, s2, 8
	s_lshl_b64 s[2:3], s[52:53], 11
	v_readlane_b32 s50, v253, 22
	v_readlane_b32 s51, v253, 23
	s_mov_b64 s[20:21], s[48:49]
	v_and_b32_e32 v144, 15, v16
	v_bfe_u32 v145, v16, 4, 2
	v_lshlrev_b32_e32 v16, 2, v16
	s_add_u32 s2, s20, s2
	v_lshlrev_b32_e32 v17, 4, v145
	v_and_b32_e32 v18, 32, v16
	v_lshlrev_b32_e32 v16, 6, v144
	s_addc_u32 s3, s21, s3
	v_or_b32_e32 v19, v17, v16
	v_bitop3_b32 v20, v17, v18, v16 bitop3:0x36
	v_lshl_add_u64 v[16:17], s[2:3], 0, v[0:1]
	s_mov_b64 s[8:9], 0x80
	s_add_i32 s7, s5, 0x18000
	v_lshl_add_u64 v[16:17], v[16:17], 0, s[8:9]
	s_mov_b32 m0, s7
	v_mov_b32_e32 v135, v1
	s_ashr_i32 s65, s64, 31
	s_waitcnt vmcnt(4)
	s_barrier
; #define STAGEA(P, br, kt) STAGE_(P, A, br, kt, so0, so1)
; #define STAGEB(P, br, kt) STAGE_(P, Bt, br, kt, sb0, sb1)
; #define WAIT_V(n) asm volatile("s_waitcnt vmcnt(" #n ")" ::: "memory")
; #define BAR __builtin_amdgcn_s_barrier()
; template <bool PERM, class EPI>
; DI void gemm256(LAS u16* shm, const u16* __restrict__ A, const u16* __restrict__ Bt, int K, int brow, int bcol, bool pre, bool has_next, int nbrow, int nbcol, EPI epi) {
;     ...
;   f32x4 acc[2][2][4][2];
; #pragma unroll
;   for (int a = 0; a < 2; ++a)
; #pragma unroll
;     for (int b = 0; b < 2; ++b)
; #pragma unroll
;       for (int m = 0; m < 4; ++m)
; #pragma unroll
;         for (int n = 0; n < 2; ++n) { acc[a][b][m][n][0] = 0.f; acc[a][b][m][n][1] = 0.f; acc[a][b][m][n][2] = 0.f; acc[a][b][m][n][3] = 0.f; }
;   bf16x8 At[4][2], B0[2][2], B1[2][2];
;   const int nt = K / 64;
;   if (!pre) {
;     STAGEB(SB(0, 0), bcol, 0); STAGEA(SA(0, 0), brow, 0);
;     STAGEB(SB(0, 1), bcol + 128, 0); STAGEA(SA(0, 1), brow + 128, 0);
;   }
;   if (wr == 1) BAR;
;   WAIT_V(4); BAR;
;   STAGEB(SB(1, 0), bcol, 1); STAGEA(SA(1, 0), brow, 1); STAGEB(SB(1, 1), bcol + 128, 1);
;   WAIT_V(6); BAR;
	global_load_lds_dwordx4 v[16:17], off
	v_lshl_add_u64 v[16:17], s[2:3], 0, v[134:135]
	s_add_i32 s53, s5, 0x1a000
	s_lshl_b64 s[2:3], s[64:65], 11
	v_readlane_b32 s10, v255, 19
	v_readlane_b32 s11, v255, 20
	s_add_u32 s2, s10, s2
	v_lshl_add_u64 v[16:17], v[16:17], 0, s[8:9]
	s_mov_b32 m0, s53
	s_addc_u32 s3, s11, s3
	v_mov_b32_e32 v131, v1
	global_load_lds_dwordx4 v[16:17], off
	v_lshl_add_u64 v[16:17], s[2:3], 0, v[130:131]
	s_add_i32 s56, s5, 0x8000
	v_lshl_add_u64 v[16:17], v[16:17], 0, s[8:9]
	s_mov_b32 m0, s56
	v_mov_b32_e32 v133, v1
	global_load_lds_dwordx4 v[16:17], off
	v_lshl_add_u64 v[16:17], s[2:3], 0, v[132:133]
	s_or_b32 s2, s52, 0x80
	s_ashr_i32 s3, s2, 31
	s_add_i32 s57, s5, 0xa000
	s_lshl_b64 s[2:3], s[2:3], 11
	s_add_u32 s2, s20, s2
	v_lshl_add_u64 v[16:17], v[16:17], 0, s[8:9]
	s_mov_b32 m0, s57
	s_addc_u32 s3, s21, s3
	global_load_lds_dwordx4 v[16:17], off
	v_lshl_add_u64 v[16:17], s[2:3], 0, v[0:1]
	s_add_i32 s59, s5, 0x1c000
	v_lshl_add_u64 v[16:17], v[16:17], 0, s[8:9]
	s_mov_b32 m0, s59
	s_add_i32 s60, s5, 0x1e000
	global_load_lds_dwordx4 v[16:17], off
	v_lshl_add_u64 v[16:17], s[2:3], 0, v[134:135]
	v_lshl_add_u64 v[16:17], v[16:17], 0, s[8:9]
	s_mov_b32 m0, s60
	s_mov_b32 s2, 0x14000
	global_load_lds_dwordx4 v[16:17], off
	v_lshlrev_b32_e32 v16, 14, v2
	v_bitop3_b32 v22, v19, s2, v18 bitop3:0xde
	s_mov_b32 s2, 0x1c000
	v_and_b32_e32 v16, 0xffff8000, v16
	v_and_b32_e32 v2, 1, v2
	v_bitop3_b32 v21, v19, s90, v18 bitop3:0xde
	v_bitop3_b32 v23, v19, s75, v18 bitop3:0xde
	v_bitop3_b32 v18, v19, s2, v18 bitop3:0xde
	s_add_i32 s2, s70, s63
	v_lshl_add_u32 v8, v8, 11, v16
	v_lshlrev_b32_e32 v2, 6, v2
	s_ashr_i32 s3, s2, 31
	v_or_b32_e32 v8, v8, v2
	v_lshlrev_b32_e32 v11, 1, v11
	s_lshl_b32 s65, s55, 12
	s_lshl_b32 s68, s54, 13
	s_lshl_b64 s[2:3], s[2:3], 11
	v_add_u32_e32 v16, v8, v11
	v_lshlrev_b32_e32 v8, 14, v4
	s_add_u32 s2, s20, s2
	v_and_b32_e32 v8, 0xffff8000, v8
	v_and_b32_e32 v4, 1, v4
	v_mov_b32_e32 v17, v1
	s_addc_u32 s3, s21, s3
	v_lshl_add_u32 v8, v14, 11, v8
	v_lshlrev_b32_e32 v4, 6, v4
	v_lshl_add_u64 v[136:137], s[2:3], 0, v[16:17]
	v_or_b32_e32 v8, v8, v4
	v_lshlrev_b32_e32 v16, 1, v15
	v_add_u32_e32 v14, v8, v16
	v_mov_b32_e32 v15, v1
	v_add_u32_e32 v7, v7, v9
	s_waitcnt vmcnt(6)
	v_lshl_add_u64 v[138:139], s[2:3], 0, v[14:15]
	s_lshl_b32 s2, s61, 10
	v_add3_u32 v7, v7, v10, v12
	s_or_b32 s2, s2, s62
	v_lshl_or_b32 v2, v7, 11, v2
	v_writelane_b32 v255, s63, 34
	s_ashr_i32 s3, s2, 31
	v_add_u32_e32 v8, v2, v11
	v_add_u32_e32 v2, v3, v13
	s_lshl_b64 s[2:3], s[2:3], 11
	v_readlane_b32 s8, v255, 9
	v_add3_u32 v2, v2, v5, v6
	v_readlane_b32 s9, v255, 10
	s_add_u32 s2, s8, s2
	v_lshl_or_b32 v2, v2, 11, v4
	s_waitcnt vmcnt(6)
	s_addc_u32 s3, s9, s3
	v_add_u32_e32 v2, v2, v16
	v_mov_b32_e32 v3, v1
	v_mov_b32_e32 v9, v1
	v_lshl_add_u64 v[142:143], s[2:3], 0, v[2:3]
	v_mov_b32_e32 v2, 0
	v_lshl_add_u64 v[140:141], s[2:3], 0, v[8:9]
	s_mov_b32 s62, -2
	s_mov_b64 s[2:3], 0
	s_add_i32 s63, s5, 0xc000
	s_add_i32 s61, s5, 0xe000
	v_add_u32_e32 v150, s65, v21
	v_add_u32_e32 v146, s68, v20
	v_add_u32_e32 v149, s65, v22
	v_add_u32_e32 v148, s65, v23
	v_add_u32_e32 v147, s65, v18
	v_mov_b32_e32 v3, v2
	v_mov_b32_e32 v4, v2
	v_mov_b32_e32 v5, v2
	v_mov_b32_e32 v6, v2
	v_mov_b32_e32 v7, v2
	v_mov_b32_e32 v8, v2
	v_mov_b32_e32 v9, v2
	v_mov_b32_e32 v10, v2
	v_mov_b32_e32 v11, v2
	v_mov_b32_e32 v12, v2
	v_mov_b32_e32 v13, v2
	v_mov_b32_e32 v14, v2
	v_mov_b32_e32 v15, v2
	v_mov_b32_e32 v16, v2
	v_mov_b32_e32 v17, v2
	v_mov_b32_e32 v18, v2
	v_mov_b32_e32 v19, v2
	v_mov_b32_e32 v20, v2
	v_mov_b32_e32 v21, v2
	v_mov_b32_e32 v22, v2
	v_mov_b32_e32 v23, v2
	v_mov_b32_e32 v24, v2
	v_mov_b32_e32 v25, v2
	v_mov_b32_e32 v26, v2
	v_mov_b32_e32 v27, v2
	v_mov_b32_e32 v28, v2
	v_mov_b32_e32 v29, v2
	v_mov_b32_e32 v30, v2
	v_mov_b32_e32 v31, v2
	v_mov_b32_e32 v32, v2
	v_mov_b32_e32 v33, v2
	v_mov_b32_e32 v34, v2
	v_mov_b32_e32 v35, v2
	v_mov_b32_e32 v36, v2
	v_mov_b32_e32 v37, v2
	v_mov_b32_e32 v38, v2
	v_mov_b32_e32 v39, v2
	v_mov_b32_e32 v40, v2
	v_mov_b32_e32 v41, v2
	v_mov_b32_e32 v42, v2
	v_mov_b32_e32 v43, v2
	v_mov_b32_e32 v44, v2
	v_mov_b32_e32 v45, v2
	v_mov_b32_e32 v46, v2
	v_mov_b32_e32 v47, v2
	v_mov_b32_e32 v48, v2
	v_mov_b32_e32 v49, v2
	v_mov_b32_e32 v50, v2
	v_mov_b32_e32 v51, v2
	v_mov_b32_e32 v52, v2
	v_mov_b32_e32 v53, v2
	v_mov_b32_e32 v54, v2
	v_mov_b32_e32 v55, v2
	v_mov_b32_e32 v56, v2
	v_mov_b32_e32 v57, v2
	v_mov_b32_e32 v58, v2
	v_mov_b32_e32 v59, v2
	v_mov_b32_e32 v60, v2
	v_mov_b32_e32 v61, v2
	v_mov_b32_e32 v62, v2
	v_mov_b32_e32 v63, v2
	v_mov_b32_e32 v64, v2
	v_mov_b32_e32 v65, v2
	v_mov_b32_e32 v66, v2
	v_mov_b32_e32 v67, v2
	v_mov_b32_e32 v68, v2
	v_mov_b32_e32 v69, v2
	v_mov_b32_e32 v70, v2
	v_mov_b32_e32 v71, v2
	v_mov_b32_e32 v72, v2
	v_mov_b32_e32 v73, v2
	v_mov_b32_e32 v74, v2
	v_mov_b32_e32 v75, v2
	v_mov_b32_e32 v76, v2
	v_mov_b32_e32 v77, v2
	v_mov_b32_e32 v78, v2
	v_mov_b32_e32 v79, v2
	v_mov_b32_e32 v80, v2
	v_mov_b32_e32 v81, v2
	v_mov_b32_e32 v82, v2
	v_mov_b32_e32 v83, v2
	v_mov_b32_e32 v84, v2
	v_mov_b32_e32 v85, v2
	v_mov_b32_e32 v86, v2
	v_mov_b32_e32 v87, v2
	v_mov_b32_e32 v88, v2
	v_mov_b32_e32 v89, v2
	v_mov_b32_e32 v90, v2
	v_mov_b32_e32 v91, v2
	v_mov_b32_e32 v92, v2
	v_mov_b32_e32 v93, v2
	v_mov_b32_e32 v94, v2
	v_mov_b32_e32 v95, v2
	v_mov_b32_e32 v96, v2
	v_mov_b32_e32 v97, v2
	v_mov_b32_e32 v98, v2
	v_mov_b32_e32 v99, v2
	v_mov_b32_e32 v100, v2
	v_mov_b32_e32 v101, v2
	v_mov_b32_e32 v102, v2
	v_mov_b32_e32 v103, v2
	v_mov_b32_e32 v104, v2
	v_mov_b32_e32 v105, v2
	v_mov_b32_e32 v106, v2
	v_mov_b32_e32 v107, v2
	v_mov_b32_e32 v108, v2
	v_mov_b32_e32 v109, v2
	v_mov_b32_e32 v110, v2
	v_mov_b32_e32 v111, v2
	v_mov_b32_e32 v112, v2
	v_mov_b32_e32 v113, v2
	v_mov_b32_e32 v114, v2
	v_mov_b32_e32 v115, v2
	v_mov_b32_e32 v116, v2
	v_mov_b32_e32 v117, v2
	v_mov_b32_e32 v118, v2
	v_mov_b32_e32 v119, v2
	v_mov_b32_e32 v120, v2
	v_mov_b32_e32 v121, v2
	v_mov_b32_e32 v122, v2
	v_mov_b32_e32 v123, v2
	v_mov_b32_e32 v124, v2
	v_mov_b32_e32 v125, v2
	v_mov_b32_e32 v126, v2
	v_mov_b32_e32 v127, v2
	v_mov_b32_e32 v128, v2
	v_mov_b32_e32 v129, v2
	v_readlane_b32 s37, v253, 9
	v_readlane_b32 s38, v253, 10
	v_readlane_b32 s39, v253, 11
	v_readlane_b32 s40, v253, 12
	v_readlane_b32 s41, v253, 13
	v_readlane_b32 s42, v253, 14
	v_readlane_b32 s43, v253, 15
	v_readlane_b32 s44, v253, 16
	v_readlane_b32 s45, v253, 17
	v_readlane_b32 s46, v253, 18
	v_readlane_b32 s47, v253, 19
	s_mov_b64 s[22:23], s[50:51]
	s_barrier
